# q-up prep epilogue: second cos/sin table load pair of each rotary block issued with the first (one round trip per block instead of two)
# baseline (speedup 1.0000x reference)
.LBB0_743:
	s_or_b64 exec, exec, s[0:1]
	s_lshl_b32 s1, s8, 7
	s_and_b32 s10, s1, 0x3f80
	v_ashrrev_i32_e32 v5, 3, v198
	s_waitcnt lgkmcnt(0)
	v_lshlrev_b32_e32 v0, 4, v198
	v_readlane_b32 s14, v254, 31
	s_and_b32 s0, s8, 0xffffff80
	v_add_u32_e32 v44, s10, v5
	v_and_b32_e32 v192, 0x70, v0
	v_readlane_b32 s15, v254, 32
	v_add_u32_e32 v0, s0, v5
	v_add_u32_e32 v46, 32, v44
	v_lshl_add_u64 v[26:27], s[14:15], 0, v[192:193]
	v_mad_i64_i32 v[2:3], s[8:9], v44, s16, v[26:27]
	v_ashrrev_i32_e32 v1, 31, v0
	v_mad_i64_i32 v[10:11], s[8:9], v46, s16, v[26:27]
	v_lshlrev_b64 v[34:35], 9, v[0:1]
	s_mov_b64 s[8:9], 0x4000
	v_add_u32_e32 v47, 64, v44
	v_readlane_b32 s24, v254, 33
	v_lshl_add_u64 v[36:37], v[34:35], 0, s[8:9]
	v_mad_i64_i32 v[18:19], s[8:9], v47, s16, v[26:27]
	v_readlane_b32 s25, v254, 34
	s_mov_b64 s[8:9], 0x8000
	v_lshl_add_u64 v[38:39], v[34:35], 0, s[8:9]
	v_lshl_add_u64 v[30:31], s[24:25], 0, v[192:193]
	v_lshl_add_u64 v[6:7], v[30:31], 0, v[34:35]
	v_lshl_add_u64 v[14:15], v[30:31], 0, v[36:37]
	v_lshl_add_u64 v[22:23], v[30:31], 0, v[38:39]
	global_load_dwordx4 v[0:3], v[2:3], off
	s_nop 0
	global_load_dwordx4 v[6:9], v[6:7], off
	s_nop 0
	global_load_dwordx4 v[10:13], v[10:11], off
	s_nop 0
	global_load_dwordx4 v[14:17], v[14:15], off
	s_nop 0
	global_load_dwordx4 v[18:21], v[18:19], off
	s_nop 0
	global_load_dwordx4 v[22:25], v[22:23], off
	v_add_u32_e32 v48, 0x60, v44
	v_mad_i64_i32 v[26:27], s[8:9], v48, s16, v[26:27]
	global_load_dwordx4 v[26:29], v[26:27], off
	s_mov_b64 s[8:9], 0xc000
	v_lshl_add_u64 v[40:41], v[34:35], 0, s[8:9]
	v_lshl_add_u64 v[30:31], v[30:31], 0, v[40:41]
	global_load_dwordx4 v[30:33], v[30:31], off
	v_bfe_u32 v78, v198, 5, 1
	v_mov_b64_e32 v[42:43], s[14:15]
	v_and_b32_e32 v45, 0x5f, v198
	v_lshlrev_b32_e32 v64, 4, v78
	v_mad_u32_u24 v65, v45, s12, v64
	v_mad_i64_i32 v[44:45], s[8:9], v44, s16, v[42:43]
	v_lshl_add_u64 v[144:145], v[44:45], 0, v[192:193]
	v_lshl_add_u64 v[34:35], s[24:25], 0, v[34:35]
	v_mad_i64_i32 v[44:45], s[8:9], v46, s16, v[42:43]
	v_mad_i64_i32 v[46:47], s[8:9], v47, s16, v[42:43]
	v_mad_i64_i32 v[42:43], s[8:9], v48, s16, v[42:43]
	v_lshl_add_u64 v[146:147], v[34:35], 0, v[192:193]
	v_lshl_add_u64 v[148:149], v[44:45], 0, v[192:193]
	v_lshl_add_u64 v[34:35], s[24:25], 0, v[36:37]
	v_lshl_add_u64 v[36:37], s[24:25], 0, v[38:39]
	v_lshl_add_u64 v[38:39], s[24:25], 0, v[40:41]
	v_lshl_add_u64 v[150:151], v[46:47], 0, v[192:193]
	v_lshl_add_u64 v[152:153], v[42:43], 0, v[192:193]
	global_load_dwordx4 v[70:73], v[144:145], off offset:128
	global_load_dwordx4 v[74:77], v[146:147], off offset:128
	v_lshl_add_u64 v[154:155], v[34:35], 0, v[192:193]
	v_lshl_add_u64 v[156:157], v[36:37], 0, v[192:193]
	v_lshl_add_u64 v[158:159], v[38:39], 0, v[192:193]
	global_load_dwordx4 v[80:83], v[148:149], off offset:128
	global_load_dwordx4 v[84:87], v[154:155], off offset:128
	global_load_dwordx4 v[88:91], v[150:151], off offset:128
	global_load_dwordx4 v[92:95], v[156:157], off offset:128
	global_load_dwordx4 v[96:99], v[152:153], off offset:128
	global_load_dwordx4 v[100:103], v[158:159], off offset:128
	v_mad_u64_u32 v[68:69], s[8:9], v5, s12, v[192:193]
	v_and_b32_e32 v49, 31, v198
	s_movk_i32 s1, 0xffc0
	v_and_or_b32 v79, v4, s1, v49
	v_mad_u64_u32 v[66:67], s[8:9], v79, s12, v[64:65]
	v_add_u32_e32 v67, 0xd800, v68
	v_and_or_b32 v192, v198, 64, s0
	s_movk_i32 s0, 0xffab
	s_waitcnt vmcnt(15)
	ds_write_b128 v68, v[0:3]
	s_waitcnt vmcnt(14)
	ds_write_b128 v68, v[6:9] offset:18432
	s_waitcnt vmcnt(13)
	ds_write_b128 v68, v[10:13] offset:4608
	s_waitcnt vmcnt(11)
	ds_write_b128 v68, v[18:21] offset:9216
	s_waitcnt vmcnt(9)
	ds_write_b128 v68, v[26:29] offset:13824
	ds_write_b128 v68, v[14:17] offset:23040
	ds_write_b128 v68, v[22:25] offset:27648
	s_waitcnt vmcnt(8)
	ds_write_b128 v68, v[30:33] offset:32256
	s_waitcnt lgkmcnt(0)
	s_barrier
	ds_read_b128 v[0:3], v65 offset:18432
	ds_read_b128 v[4:7], v66
	ds_read_b128 v[104:107], v65 offset:18464
	ds_read_b128 v[108:111], v66 offset:32
	ds_read_b128 v[8:11], v66 offset:4608
	ds_read_b128 v[112:115], v66 offset:4640
	s_waitcnt lgkmcnt(4)
	v_mfma_f32_32x32x16_bf16 v[48:63], v[0:3], v[4:7], 0
	s_waitcnt lgkmcnt(1)
	v_mfma_f32_32x32x16_bf16 v[16:31], v[0:3], v[8:11], 0
	ds_read_b128 v[0:3], v65 offset:23040
	ds_read_b128 v[116:119], v65 offset:23072
	s_waitcnt lgkmcnt(1)
	v_mfma_f32_32x32x16_bf16 v[32:47], v[0:3], v[4:7], 0
	v_mfma_f32_32x32x16_bf16 v[0:15], v[0:3], v[8:11], 0
	v_mfma_f32_32x32x16_bf16 v[48:63], v[104:107], v[108:111], v[48:63]
	v_mfma_f32_32x32x16_bf16 v[16:31], v[104:107], v[112:115], v[16:31]
	s_waitcnt lgkmcnt(0)
	v_mfma_f32_32x32x16_bf16 v[32:47], v[116:119], v[108:111], v[32:47]
	v_mfma_f32_32x32x16_bf16 v[0:15], v[116:119], v[112:115], v[0:15]
	ds_read_b128 v[104:107], v65 offset:18496
	ds_read_b128 v[108:111], v66 offset:64
	ds_read_b128 v[112:115], v65 offset:18528
	ds_read_b128 v[116:119], v66 offset:96
	ds_read_b128 v[120:123], v66 offset:4672
	ds_read_b128 v[124:127], v66 offset:4704
	s_waitcnt lgkmcnt(4)
	v_mfma_f32_32x32x16_bf16 v[48:63], v[104:107], v[108:111], v[48:63]
	s_waitcnt lgkmcnt(1)
	v_mfma_f32_32x32x16_bf16 v[16:31], v[104:107], v[120:123], v[16:31]
	ds_read_b128 v[104:107], v65 offset:23104
	ds_read_b128 v[128:131], v65 offset:23136
	s_waitcnt lgkmcnt(1)
	v_mfma_f32_32x32x16_bf16 v[32:47], v[104:107], v[108:111], v[32:47]
	v_mfma_f32_32x32x16_bf16 v[0:15], v[104:107], v[120:123], v[0:15]
	v_mfma_f32_32x32x16_bf16 v[48:63], v[112:115], v[116:119], v[48:63]
	v_mfma_f32_32x32x16_bf16 v[16:31], v[112:115], v[124:127], v[16:31]
	s_waitcnt lgkmcnt(0)
	v_mfma_f32_32x32x16_bf16 v[32:47], v[128:131], v[116:119], v[32:47]
	global_load_dwordx4 v[104:107], v[144:145], off offset:256
	global_load_dwordx4 v[108:111], v[146:147], off offset:256
	global_load_dwordx4 v[112:115], v[148:149], off offset:256
	global_load_dwordx4 v[116:119], v[154:155], off offset:256
	global_load_dwordx4 v[120:123], v[150:151], off offset:256
	global_load_dwordx4 v[132:135], v[156:157], off offset:256
	global_load_dwordx4 v[136:139], v[152:153], off offset:256
	global_load_dwordx4 v[140:143], v[158:159], off offset:256
	s_waitcnt vmcnt(15)
	ds_write_b128 v68, v[70:73] offset:36864
	s_waitcnt vmcnt(14)
	ds_write_b128 v68, v[74:77] offset:55296
	s_waitcnt vmcnt(13)
	ds_write_b128 v68, v[80:83] offset:41472
	s_waitcnt vmcnt(12)
	ds_write_b128 v68, v[84:87] offset:59904
	s_waitcnt vmcnt(11)
	ds_write_b128 v68, v[88:91] offset:46080
	s_waitcnt vmcnt(10)
	ds_write_b128 v68, v[92:95] offset:64512
	s_waitcnt vmcnt(9)
	ds_write_b128 v68, v[96:99] offset:50688
	s_waitcnt vmcnt(8)
	ds_write_b128 v67, v[100:103] offset:13824
	s_waitcnt lgkmcnt(0)
	s_barrier
	ds_read_b128 v[70:73], v65 offset:55296
	ds_read_b128 v[74:77], v66 offset:36864
	ds_read_b128 v[80:83], v65 offset:55328
	ds_read_b128 v[84:87], v66 offset:36896
	v_mfma_f32_32x32x16_bf16 v[0:15], v[128:131], v[124:127], v[0:15]
	ds_read_b128 v[88:91], v66 offset:41472
	ds_read_b128 v[92:95], v66 offset:41504
	s_waitcnt lgkmcnt(4)
	v_mfma_f32_32x32x16_bf16 v[48:63], v[70:73], v[74:77], v[48:63]
	s_waitcnt lgkmcnt(1)
	v_mfma_f32_32x32x16_bf16 v[16:31], v[70:73], v[88:91], v[16:31]
	ds_read_b128 v[70:73], v65 offset:59904
	ds_read_b128 v[96:99], v65 offset:59936
	s_waitcnt lgkmcnt(1)
	v_mfma_f32_32x32x16_bf16 v[32:47], v[70:73], v[74:77], v[32:47]
	v_mfma_f32_32x32x16_bf16 v[0:15], v[70:73], v[88:91], v[0:15]
	v_mfma_f32_32x32x16_bf16 v[48:63], v[80:83], v[84:87], v[48:63]
	v_mfma_f32_32x32x16_bf16 v[16:31], v[80:83], v[92:95], v[16:31]
	s_waitcnt lgkmcnt(0)
	v_mfma_f32_32x32x16_bf16 v[32:47], v[96:99], v[84:87], v[32:47]
	ds_read_b128 v[70:73], v65 offset:55360
	ds_read_b128 v[74:77], v66 offset:36928
	ds_read_b128 v[80:83], v65 offset:55392
	ds_read_b128 v[84:87], v66 offset:36960
	v_mfma_f32_32x32x16_bf16 v[0:15], v[96:99], v[92:95], v[0:15]
	ds_read_b128 v[88:91], v66 offset:41536
	ds_read_b128 v[92:95], v66 offset:41568
	s_waitcnt lgkmcnt(4)
	v_mfma_f32_32x32x16_bf16 v[48:63], v[70:73], v[74:77], v[48:63]
	s_waitcnt lgkmcnt(1)
	v_mfma_f32_32x32x16_bf16 v[16:31], v[70:73], v[88:91], v[16:31]
	ds_read_b128 v[70:73], v65 offset:59968
	ds_read_b128 v[96:99], v65 offset:60000
	s_waitcnt lgkmcnt(1)
	v_mfma_f32_32x32x16_bf16 v[32:47], v[70:73], v[74:77], v[32:47]
	v_mfma_f32_32x32x16_bf16 v[0:15], v[70:73], v[88:91], v[0:15]
	v_mfma_f32_32x32x16_bf16 v[48:63], v[80:83], v[84:87], v[48:63]
	v_mfma_f32_32x32x16_bf16 v[16:31], v[80:83], v[92:95], v[16:31]
	s_waitcnt lgkmcnt(0)
	v_mfma_f32_32x32x16_bf16 v[32:47], v[96:99], v[84:87], v[32:47]
	global_load_dwordx4 v[70:73], v[144:145], off offset:384
	global_load_dwordx4 v[74:77], v[146:147], off offset:384
	global_load_dwordx4 v[80:83], v[148:149], off offset:384
	global_load_dwordx4 v[84:87], v[154:155], off offset:384
	global_load_dwordx4 v[88:91], v[150:151], off offset:384
	global_load_dwordx4 v[100:103], v[156:157], off offset:384
	global_load_dwordx4 v[124:127], v[152:153], off offset:384
	global_load_dwordx4 v[128:131], v[158:159], off offset:384
	s_waitcnt vmcnt(15)
	ds_write_b128 v68, v[104:107]
	s_waitcnt vmcnt(14)
	ds_write_b128 v68, v[108:111] offset:18432
	s_waitcnt vmcnt(13)
	ds_write_b128 v68, v[112:115] offset:4608
	s_waitcnt vmcnt(12)
	ds_write_b128 v68, v[116:119] offset:23040
	s_waitcnt vmcnt(11)
	ds_write_b128 v68, v[120:123] offset:9216
	s_waitcnt vmcnt(10)
	ds_write_b128 v68, v[132:135] offset:27648
	s_waitcnt vmcnt(9)
	ds_write_b128 v68, v[136:139] offset:13824
	s_waitcnt vmcnt(8)
	ds_write_b128 v68, v[140:143] offset:32256
	s_waitcnt lgkmcnt(0)
	s_barrier
	v_mfma_f32_32x32x16_bf16 v[0:15], v[96:99], v[92:95], v[0:15]
	ds_read_b128 v[92:95], v65 offset:18432
	ds_read_b128 v[96:99], v66
	ds_read_b128 v[104:107], v65 offset:18464
	ds_read_b128 v[108:111], v66 offset:32
	ds_read_b128 v[112:115], v66 offset:4608
	ds_read_b128 v[116:119], v66 offset:4640
	s_waitcnt lgkmcnt(4)
	v_mfma_f32_32x32x16_bf16 v[48:63], v[92:95], v[96:99], v[48:63]
	s_waitcnt lgkmcnt(1)
	v_mfma_f32_32x32x16_bf16 v[16:31], v[92:95], v[112:115], v[16:31]
	ds_read_b128 v[92:95], v65 offset:23040
	ds_read_b128 v[120:123], v65 offset:23072
	s_waitcnt lgkmcnt(1)
	v_mfma_f32_32x32x16_bf16 v[32:47], v[92:95], v[96:99], v[32:47]
	v_mfma_f32_32x32x16_bf16 v[0:15], v[92:95], v[112:115], v[0:15]
	v_mfma_f32_32x32x16_bf16 v[48:63], v[104:107], v[108:111], v[48:63]
	v_mfma_f32_32x32x16_bf16 v[16:31], v[104:107], v[116:119], v[16:31]
	s_waitcnt lgkmcnt(0)
	v_mfma_f32_32x32x16_bf16 v[32:47], v[120:123], v[108:111], v[32:47]
	ds_read_b128 v[92:95], v65 offset:18496
	ds_read_b128 v[96:99], v66 offset:64
	ds_read_b128 v[104:107], v65 offset:18528
	ds_read_b128 v[108:111], v66 offset:96
	v_mfma_f32_32x32x16_bf16 v[0:15], v[120:123], v[116:119], v[0:15]
	ds_read_b128 v[112:115], v66 offset:4672
	ds_read_b128 v[116:119], v66 offset:4704
	s_waitcnt lgkmcnt(4)
	v_mfma_f32_32x32x16_bf16 v[48:63], v[92:95], v[96:99], v[48:63]
	s_waitcnt lgkmcnt(1)
	v_mfma_f32_32x32x16_bf16 v[16:31], v[92:95], v[112:115], v[16:31]
	ds_read_b128 v[92:95], v65 offset:23104
	ds_read_b128 v[120:123], v65 offset:23136
	s_waitcnt vmcnt(7)
	ds_write_b128 v68, v[70:73] offset:36864
	s_waitcnt vmcnt(6)
	ds_write_b128 v68, v[74:77] offset:55296
	s_waitcnt vmcnt(5)
	ds_write_b128 v68, v[80:83] offset:41472
	s_waitcnt vmcnt(4)
	ds_write_b128 v68, v[84:87] offset:59904
	s_waitcnt vmcnt(3)
	ds_write_b128 v68, v[88:91] offset:46080
	s_waitcnt vmcnt(2)
	ds_write_b128 v68, v[100:103] offset:64512
	s_waitcnt vmcnt(1)
	ds_write_b128 v68, v[124:127] offset:50688
	s_waitcnt vmcnt(0)
	ds_write_b128 v67, v[128:131] offset:13824
	s_waitcnt lgkmcnt(0)
	s_barrier
	ds_read_b128 v[68:71], v65 offset:55296
	ds_read_b128 v[72:75], v66 offset:36864
	ds_read_b128 v[80:83], v65 offset:55328
	ds_read_b128 v[84:87], v66 offset:36896
	v_mfma_f32_32x32x16_bf16 v[32:47], v[92:95], v[96:99], v[32:47]
	v_mfma_f32_32x32x16_bf16 v[0:15], v[92:95], v[112:115], v[0:15]
	ds_read_b128 v[88:91], v66 offset:41472
	ds_read_b128 v[92:95], v66 offset:41504
	v_mfma_f32_32x32x16_bf16 v[48:63], v[104:107], v[108:111], v[48:63]
	v_mfma_f32_32x32x16_bf16 v[16:31], v[104:107], v[116:119], v[16:31]
	v_mfma_f32_32x32x16_bf16 v[32:47], v[120:123], v[108:111], v[32:47]
	v_mfma_f32_32x32x16_bf16 v[0:15], v[120:123], v[116:119], v[0:15]
	s_waitcnt lgkmcnt(4)
	v_mfma_f32_32x32x16_bf16 v[48:63], v[68:71], v[72:75], v[48:63]
	s_waitcnt lgkmcnt(1)
	v_mfma_f32_32x32x16_bf16 v[16:31], v[68:71], v[88:91], v[16:31]
	ds_read_b128 v[68:71], v65 offset:59904
	ds_read_b128 v[96:99], v65 offset:59936
	s_waitcnt lgkmcnt(1)
	v_mfma_f32_32x32x16_bf16 v[32:47], v[68:71], v[72:75], v[32:47]
	v_mfma_f32_32x32x16_bf16 v[0:15], v[68:71], v[88:91], v[0:15]
	v_mfma_f32_32x32x16_bf16 v[48:63], v[80:83], v[84:87], v[48:63]
	v_mfma_f32_32x32x16_bf16 v[16:31], v[80:83], v[92:95], v[16:31]
	s_waitcnt lgkmcnt(0)
	v_mfma_f32_32x32x16_bf16 v[32:47], v[96:99], v[84:87], v[32:47]
	ds_read_b128 v[68:71], v65 offset:55360
	ds_read_b128 v[72:75], v66 offset:36928
	ds_read_b128 v[80:83], v65 offset:55392
	ds_read_b128 v[84:87], v66 offset:36960
	v_mfma_f32_32x32x16_bf16 v[0:15], v[96:99], v[92:95], v[0:15]
	ds_read_b128 v[88:91], v66 offset:41536
	ds_read_b128 v[92:95], v66 offset:41568
	s_waitcnt lgkmcnt(4)
	v_mfma_f32_32x32x16_bf16 v[48:63], v[68:71], v[72:75], v[48:63]
	s_waitcnt lgkmcnt(1)
	v_mfma_f32_32x32x16_bf16 v[16:31], v[68:71], v[88:91], v[16:31]
	ds_read_b128 v[66:69], v65 offset:59968
	ds_read_b128 v[96:99], v65 offset:60000
	v_lshl_add_u32 v65, v79, 2, v232
	s_waitcnt lgkmcnt(0)
	s_barrier
	v_mfma_f32_32x32x16_bf16 v[32:47], v[66:69], v[72:75], v[32:47]
	v_mfma_f32_32x32x16_bf16 v[0:15], v[66:69], v[88:91], v[0:15]
	ds_read_b32 v66, v65
	v_lshlrev_b32_e32 v67, 2, v78
	v_add_u32_e32 v65, s10, v79
	v_lshlrev_b32_e32 v88, 4, v65
	v_ashrrev_i32_e32 v89, 31, v88
	v_mfma_f32_32x32x16_bf16 v[48:63], v[80:83], v[84:87], v[48:63]
	v_mfma_f32_32x32x16_bf16 v[16:31], v[80:83], v[92:95], v[16:31]
	s_nop 0
	s_nop 9
	s_waitcnt lgkmcnt(0)
	v_mul_f32_e64 v74, v48, v66
	v_mul_f32_e64 v75, v49, v66
	v_lshrrev_b32_e32 v48, 5, v192
	v_mov_b32_e32 v49, 0xffffffaa
	v_mad_legacy_u16 v48, v48, s0, v49
	v_and_b32_e32 v48, 0xfe, v48
	s_movk_i32 s0, 0x55
	v_cmp_gt_u16_e32 vcc, s0, v48
	v_mfma_f32_32x32x16_bf16 v[32:47], v[96:99], v[84:87], v[32:47]
	v_readlane_b32 s0, v254, 21
	v_mul_f32_e64 v76, v50, v66
	v_mul_f32_e64 v77, v51, v66
	v_lshlrev_b64 v[50:51], 2, v[88:89]
	v_readlane_b32 s1, v254, 22
	v_pk_mul_f32 v[72:73], v[52:53], v[66:67] op_sel_hi:[1,0]
	v_mul_f32_e32 v68, v54, v66
	v_lshl_add_u64 v[52:53], s[0:1], 0, v[50:51]
	v_mfma_f32_32x32x16_bf16 v[0:15], v[96:99], v[92:95], v[0:15]
	v_readlane_b32 s0, v254, 23
	v_mov_b32_e32 v54, v63
	v_readlane_b32 s1, v254, 24
	v_mul_f32_e64 v56, v56, v66
	v_mul_f32_e64 v57, v57, v66
	v_pk_mul_f32 v[58:59], v[58:59], v[66:67] op_sel_hi:[1,0]
	v_pk_mul_f32 v[60:61], v[60:61], v[66:67] op_sel_hi:[1,0]
	v_mul_f32_e32 v70, v62, v66
	v_pk_mul_f32 v[62:63], v[54:55], v[66:67] op_sel_hi:[1,0]
	v_lshlrev_b32_e32 v48, 2, v67
	v_lshl_add_u64 v[50:51], s[0:1], 0, v[50:51]
	s_and_saveexec_b64 s[0:1], vcc
	s_cbranch_execz .LBB0_745
	v_mov_b32_e32 v49, v193
	v_lshl_add_u64 v[54:55], v[52:53], 0, v[48:49]
	v_lshl_add_u64 v[88:89], v[50:51], 0, v[48:49]
	global_load_dwordx4 v[80:83], v[54:55], off
	global_load_dwordx4 v[84:87], v[88:89], off
	global_load_dwordx4 v[160:163], v[54:55], off offset:32
	global_load_dwordx4 v[164:167], v[88:89], off offset:32
	v_mov_b32_e32 v71, v62
	v_mov_b32_e32 v69, v63
	s_waitcnt vmcnt(2) lgkmcnt(0)
	v_pk_mul_f32 v[90:91], v[56:57], v[84:85]
	s_nop 0
	v_pk_fma_f32 v[90:91], v[74:75], v[80:81], v[90:91] neg_lo:[0,0,1] neg_hi:[0,0,1]
	v_pk_mul_f32 v[74:75], v[74:75], v[84:85]
	s_nop 0
	v_pk_fma_f32 v[56:57], v[56:57], v[80:81], v[74:75]
	v_pk_mul_f32 v[74:75], v[58:59], v[86:87]
	s_nop 0
	v_pk_fma_f32 v[84:85], v[76:77], v[82:83], v[74:75] neg_lo:[0,0,1] neg_hi:[0,0,1]
	v_pk_mul_f32 v[74:75], v[76:77], v[86:87]
	s_nop 0
	v_pk_fma_f32 v[58:59], v[58:59], v[82:83], v[74:75]
	s_waitcnt vmcnt(0)
	v_pk_mul_f32 v[54:55], v[60:61], v[164:165]
	s_nop 0
	v_pk_fma_f32 v[54:55], v[72:73], v[160:161], v[54:55] neg_lo:[0,0,1] neg_hi:[0,0,1]
	v_pk_mul_f32 v[72:73], v[72:73], v[164:165]
	s_nop 0
	v_pk_fma_f32 v[60:61], v[60:61], v[160:161], v[72:73]
	v_mul_f32_e32 v72, v68, v166
	v_mul_f32_e32 v74, v70, v162
	v_pk_mul_f32 v[70:71], v[70:71], v[166:167]
	v_mov_b32_e32 v82, v163
	v_mov_b32_e32 v83, v167
	v_pk_mul_f32 v[62:63], v[62:63], v[82:83]
	v_pk_fma_f32 v[68:69], v[68:69], v[162:163], v[70:71] neg_lo:[0,0,1] neg_hi:[0,0,1]
	v_mov_b32_e32 v75, v62
	v_mov_b32_e32 v73, v63
	v_pk_add_f32 v[70:71], v[74:75], v[72:73]
	v_mov_b32_e32 v74, v90
	v_mov_b32_e32 v75, v91
	v_mov_b32_e32 v76, v84
	v_mov_b32_e32 v77, v85
	v_mov_b32_e32 v72, v54
	v_mov_b32_e32 v73, v55
	v_mov_b32_e32 v63, v69
	v_mov_b32_e32 v62, v71
	v_mov_b32_e32 v80, v164
	v_mov_b32_e32 v81, v165
.LBB0_745:
	s_or_b64 exec, exec, s[0:1]
	v_readlane_b32 s0, v253, 61
	v_readlane_b32 s1, v253, 62
	v_cvt_pk_bf16_f32 v56, v56, v57
	v_cvt_pk_bf16_f32 v57, v58, v59
	v_mov_b64_e32 v[54:55], s[0:1]
	v_mad_i64_i32 v[54:55], s[0:1], v65, s17, v[54:55]
	v_lshl_add_u64 v[54:55], v[192:193], 1, v[54:55]
	v_mov_b32_e32 v65, v193
	v_cvt_pk_bf16_f32 v58, v60, v61
	v_cvt_pk_bf16_f32 v59, v70, v62
	v_mov_b32_e32 v67, v66
	v_lshl_add_u64 v[54:55], v[54:55], 0, v[64:65]
	v_permlane32_swap_b32_e32 v56, v58
	v_permlane32_swap_b32_e32 v57, v59
	v_or_b32_e32 v49, 32, v192
	global_store_dwordx4 v[54:55], v[56:59], off offset:32
	v_pk_mul_f32 v[60:61], v[34:35], v[66:67]
	v_pk_mul_f32 v[34:35], v[42:43], v[66:67]
	v_pk_mul_f32 v[58:59], v[32:33], v[66:67]
	v_pk_mul_f32 v[32:33], v[40:41], v[66:67]
	v_pk_mul_f32 v[42:43], v[36:37], v[66:67]
	v_pk_mul_f32 v[36:37], v[44:45], v[66:67]
	v_lshrrev_b32_e32 v41, 5, v49
	s_movk_i32 s0, 0xffab
	v_mov_b32_e32 v44, 0xffffffaa
	v_cvt_pk_bf16_f32 v74, v74, v75
	v_cvt_pk_bf16_f32 v75, v76, v77
	v_cvt_pk_bf16_f32 v76, v72, v73
	v_cvt_pk_bf16_f32 v77, v68, v63
	v_mul_f32_e32 v56, v38, v66
	v_mov_b32_e32 v38, v47
	v_mad_legacy_u16 v41, v41, s0, v44
	s_movk_i32 s0, 0x55
	v_permlane32_swap_b32_e32 v74, v76
	v_permlane32_swap_b32_e32 v75, v77
	v_mul_f32_e32 v40, v46, v66
	v_pk_mul_f32 v[38:39], v[38:39], v[66:67]
	v_cmp_lt_u16_sdwa s[0:1], v41, s0 src0_sel:BYTE_0 src1_sel:DWORD
	global_store_dwordx4 v[54:55], v[74:77], off
	s_and_saveexec_b64 s[8:9], s[0:1]
	s_cbranch_execz .LBB0_747
	v_mov_b32_e32 v49, v193
	v_lshl_add_u64 v[62:63], v[52:53], 0, v[48:49]
	v_lshl_add_u64 v[64:65], v[50:51], 0, v[48:49]
	global_load_dwordx4 v[44:47], v[62:63], off
	global_load_dwordx4 v[50:53], v[64:65], off
	global_load_dwordx4 v[160:163], v[62:63], off offset:32
	global_load_dwordx4 v[164:167], v[64:65], off offset:32
	v_mov_b32_e32 v41, v38
	v_mov_b32_e32 v57, v39
	s_waitcnt vmcnt(2) lgkmcnt(0)
	v_pk_mul_f32 v[66:67], v[32:33], v[50:51]
	v_pk_mul_f32 v[50:51], v[58:59], v[50:51]
	v_pk_fma_f32 v[66:67], v[58:59], v[44:45], v[66:67] neg_lo:[0,0,1] neg_hi:[0,0,1]
	v_pk_fma_f32 v[32:33], v[32:33], v[44:45], v[50:51]
	v_pk_mul_f32 v[44:45], v[34:35], v[52:53]
	s_nop 0
	v_pk_fma_f32 v[68:69], v[60:61], v[46:47], v[44:45] neg_lo:[0,0,1] neg_hi:[0,0,1]
	v_pk_mul_f32 v[44:45], v[60:61], v[52:53]
	v_mov_b32_e32 v60, v68
	v_pk_fma_f32 v[34:35], v[34:35], v[46:47], v[44:45]
	v_mov_b32_e32 v61, v69
	s_waitcnt vmcnt(0)
	v_pk_mul_f32 v[58:59], v[36:37], v[164:165]
	s_nop 0
	v_pk_fma_f32 v[62:63], v[42:43], v[160:161], v[58:59] neg_lo:[0,0,1] neg_hi:[0,0,1]
	v_pk_mul_f32 v[42:43], v[42:43], v[164:165]
	v_mov_b32_e32 v58, v66
	v_pk_fma_f32 v[36:37], v[36:37], v[160:161], v[42:43]
	v_mul_f32_e32 v42, v56, v166
	v_mul_f32_e32 v44, v40, v162
	v_pk_mul_f32 v[40:41], v[40:41], v[166:167]
	v_mov_b32_e32 v52, v163
	v_mov_b32_e32 v53, v167
	v_pk_mul_f32 v[38:39], v[38:39], v[52:53]
	v_pk_fma_f32 v[56:57], v[56:57], v[162:163], v[40:41] neg_lo:[0,0,1] neg_hi:[0,0,1]
	v_mov_b32_e32 v45, v38
	v_mov_b32_e32 v43, v39
	v_pk_add_f32 v[40:41], v[44:45], v[42:43]
	v_mov_b32_e32 v59, v67
	v_mov_b32_e32 v42, v62
	v_mov_b32_e32 v43, v63
	v_mov_b32_e32 v39, v57
	v_mov_b32_e32 v38, v41
	v_mov_b32_e32 v46, v162
	v_mov_b32_e32 v47, v163
	v_mov_b32_e32 v50, v164
	v_mov_b32_e32 v51, v165
.LBB0_747:
	s_or_b64 exec, exec, s[8:9]
	v_cvt_pk_bf16_f32 v44, v58, v59
	v_cvt_pk_bf16_f32 v45, v60, v61
	v_cvt_pk_bf16_f32 v46, v42, v43
	v_cvt_pk_bf16_f32 v47, v56, v39
	v_cvt_pk_bf16_f32 v32, v32, v33
	v_cvt_pk_bf16_f32 v33, v34, v35
	v_cvt_pk_bf16_f32 v34, v36, v37
	v_cvt_pk_bf16_f32 v35, v40, v38
	v_or_b32_e32 v41, 32, v79
	v_permlane32_swap_b32_e32 v44, v46
	v_permlane32_swap_b32_e32 v45, v47
	v_permlane32_swap_b32_e32 v32, v34
	v_permlane32_swap_b32_e32 v33, v35
	global_store_dwordx4 v[54:55], v[44:47], off offset:64
	global_store_dwordx4 v[54:55], v[32:35], off offset:96
	v_add_u32_e32 v42, s10, v41
	v_lshlrev_b32_e32 v44, 4, v42
	v_lshl_add_u32 v32, v41, 2, v232
	ds_read_b32 v32, v32
	v_ashrrev_i32_e32 v45, 31, v44
	v_readlane_b32 s8, v254, 21
	v_readlane_b32 s9, v254, 22
	s_waitcnt lgkmcnt(0)
	v_pk_mul_f32 v[38:39], v[16:17], v[32:33] op_sel_hi:[1,0]
	v_lshlrev_b64 v[16:17], 2, v[44:45]
	v_pk_mul_f32 v[40:41], v[18:19], v[32:33] op_sel_hi:[1,0]
	v_lshl_add_u64 v[18:19], s[8:9], 0, v[16:17]
	v_readlane_b32 s8, v254, 23
	v_mul_f32_e32 v34, v22, v32
	v_mov_b32_e32 v22, v31
	v_readlane_b32 s9, v254, 24
	v_pk_mul_f32 v[24:25], v[24:25], v[32:33] op_sel_hi:[1,0]
	v_pk_mul_f32 v[26:27], v[26:27], v[32:33] op_sel_hi:[1,0]
	v_pk_mul_f32 v[36:37], v[20:21], v[32:33] op_sel_hi:[1,0]
	v_pk_mul_f32 v[28:29], v[28:29], v[32:33] op_sel_hi:[1,0]
	v_mul_f32_e32 v30, v30, v32
	v_pk_mul_f32 v[22:23], v[22:23], v[32:33] op_sel_hi:[1,0]
	v_lshl_add_u64 v[16:17], s[8:9], 0, v[16:17]
	s_and_saveexec_b64 s[8:9], vcc
	s_cbranch_execz .LBB0_749
	v_mov_b32_e32 v49, v193
	v_lshl_add_u64 v[20:21], v[18:19], 0, v[48:49]
	v_lshl_add_u64 v[54:55], v[16:17], 0, v[48:49]
	global_load_dwordx4 v[44:47], v[20:21], off
	global_load_dwordx4 v[50:53], v[54:55], off
	global_load_dwordx4 v[160:163], v[20:21], off offset:32
	global_load_dwordx4 v[164:167], v[54:55], off offset:32
	v_mov_b32_e32 v31, v22
	v_mov_b32_e32 v35, v23
	s_waitcnt vmcnt(2) lgkmcnt(0)
	v_pk_mul_f32 v[56:57], v[24:25], v[50:51]
	s_nop 0
	v_pk_fma_f32 v[56:57], v[38:39], v[44:45], v[56:57] neg_lo:[0,0,1] neg_hi:[0,0,1]
	v_pk_mul_f32 v[38:39], v[38:39], v[50:51]
	s_nop 0
	v_pk_fma_f32 v[24:25], v[24:25], v[44:45], v[38:39]
	v_pk_mul_f32 v[38:39], v[26:27], v[52:53]
	s_nop 0
	v_pk_fma_f32 v[50:51], v[40:41], v[46:47], v[38:39] neg_lo:[0,0,1] neg_hi:[0,0,1]
	v_pk_mul_f32 v[38:39], v[40:41], v[52:53]
	s_nop 0
	v_pk_fma_f32 v[26:27], v[26:27], v[46:47], v[38:39]
	s_waitcnt vmcnt(0)
	v_pk_mul_f32 v[20:21], v[28:29], v[164:165]
	s_nop 0
	v_pk_fma_f32 v[20:21], v[36:37], v[160:161], v[20:21] neg_lo:[0,0,1] neg_hi:[0,0,1]
	v_pk_mul_f32 v[36:37], v[36:37], v[164:165]
	s_nop 0
	v_pk_fma_f32 v[28:29], v[28:29], v[160:161], v[36:37]
	v_mul_f32_e32 v36, v34, v166
	v_mul_f32_e32 v38, v30, v162
	v_pk_mul_f32 v[30:31], v[30:31], v[166:167]
	v_mov_b32_e32 v46, v163
	v_mov_b32_e32 v47, v167
	v_pk_mul_f32 v[22:23], v[22:23], v[46:47]
	v_pk_fma_f32 v[34:35], v[34:35], v[162:163], v[30:31] neg_lo:[0,0,1] neg_hi:[0,0,1]
	v_mov_b32_e32 v39, v22
	v_mov_b32_e32 v37, v23
	v_pk_add_f32 v[30:31], v[38:39], v[36:37]
	v_mov_b32_e32 v38, v56
	v_mov_b32_e32 v39, v57
	v_mov_b32_e32 v40, v50
	v_mov_b32_e32 v41, v51
	v_mov_b32_e32 v36, v20
	v_mov_b32_e32 v37, v21
	v_mov_b32_e32 v23, v35
	v_mov_b32_e32 v22, v31
	v_mov_b32_e32 v44, v164
	v_mov_b32_e32 v45, v165
.LBB0_749:
	s_or_b64 exec, exec, s[8:9]
	v_readlane_b32 s8, v253, 61
	v_readlane_b32 s9, v253, 62
	v_lshlrev_b32_e32 v31, 3, v78
	v_cvt_pk_bf16_f32 v24, v24, v25
	v_mov_b64_e32 v[20:21], s[8:9]
	v_mad_i64_i32 v[20:21], s[8:9], v42, s17, v[20:21]
	v_lshl_add_u64 v[20:21], v[192:193], 1, v[20:21]
	v_lshlrev_b32_e32 v192, 1, v31
	v_cvt_pk_bf16_f32 v25, v26, v27
	v_cvt_pk_bf16_f32 v26, v28, v29
	v_cvt_pk_bf16_f32 v27, v30, v22
	v_mov_b32_e32 v33, v32
	v_lshl_add_u64 v[20:21], v[20:21], 0, v[192:193]
	v_cvt_pk_bf16_f32 v38, v38, v39
	v_cvt_pk_bf16_f32 v39, v40, v41
	v_cvt_pk_bf16_f32 v40, v36, v37
	v_cvt_pk_bf16_f32 v41, v34, v23
	v_permlane32_swap_b32_e32 v24, v26
	v_permlane32_swap_b32_e32 v25, v27
	v_mul_f32_e32 v22, v6, v32
	v_mov_b32_e32 v6, v15
	v_permlane32_swap_b32_e32 v38, v40
	v_permlane32_swap_b32_e32 v39, v41
	global_store_dwordx4 v[20:21], v[24:27], off offset:32
	v_pk_mul_f32 v[6:7], v[6:7], v[32:33]
	global_store_dwordx4 v[20:21], v[38:41], off
	v_pk_mul_f32 v[24:25], v[0:1], v[32:33]
	v_pk_mul_f32 v[0:1], v[8:9], v[32:33]
	v_pk_mul_f32 v[26:27], v[2:3], v[32:33]
	v_pk_mul_f32 v[2:3], v[10:11], v[32:33]
	v_pk_mul_f32 v[10:11], v[4:5], v[32:33]
	v_pk_mul_f32 v[4:5], v[12:13], v[32:33]
	v_mul_f32_e32 v8, v14, v32
	s_and_saveexec_b64 s[8:9], s[0:1]
	s_cbranch_execz .LBB0_751
	v_mov_b32_e32 v49, v193
	v_lshl_add_u64 v[28:29], v[18:19], 0, v[48:49]
	v_lshl_add_u64 v[30:31], v[16:17], 0, v[48:49]
	global_load_dwordx4 v[12:15], v[28:29], off
	global_load_dwordx4 v[16:19], v[30:31], off
	global_load_dwordx4 v[160:163], v[28:29], off offset:32
	global_load_dwordx4 v[164:167], v[30:31], off offset:32
	v_mov_b32_e32 v9, v6
	v_mov_b32_e32 v23, v7
	s_waitcnt vmcnt(2) lgkmcnt(0)
	v_pk_mul_f32 v[32:33], v[0:1], v[16:17]
	v_pk_mul_f32 v[16:17], v[24:25], v[16:17]
	v_pk_fma_f32 v[32:33], v[24:25], v[12:13], v[32:33] neg_lo:[0,0,1] neg_hi:[0,0,1]
	v_pk_fma_f32 v[0:1], v[0:1], v[12:13], v[16:17]
	v_pk_mul_f32 v[12:13], v[2:3], v[18:19]
	s_nop 0
	v_pk_fma_f32 v[34:35], v[26:27], v[14:15], v[12:13] neg_lo:[0,0,1] neg_hi:[0,0,1]
	v_pk_mul_f32 v[12:13], v[26:27], v[18:19]
	v_mov_b32_e32 v26, v34
	v_pk_fma_f32 v[2:3], v[2:3], v[14:15], v[12:13]
	v_mov_b32_e32 v27, v35
	s_waitcnt vmcnt(0)
	v_pk_mul_f32 v[24:25], v[4:5], v[164:165]
	s_nop 0
	v_pk_fma_f32 v[28:29], v[10:11], v[160:161], v[24:25] neg_lo:[0,0,1] neg_hi:[0,0,1]
	v_pk_mul_f32 v[10:11], v[10:11], v[164:165]
	v_mov_b32_e32 v24, v32
	v_pk_fma_f32 v[4:5], v[4:5], v[160:161], v[10:11]
	v_mul_f32_e32 v10, v22, v166
	v_mul_f32_e32 v12, v8, v162
	v_pk_mul_f32 v[8:9], v[8:9], v[166:167]
	v_mov_b32_e32 v18, v163
	v_mov_b32_e32 v19, v167
	v_pk_mul_f32 v[6:7], v[6:7], v[18:19]
	v_pk_fma_f32 v[22:23], v[22:23], v[162:163], v[8:9] neg_lo:[0,0,1] neg_hi:[0,0,1]
	v_mov_b32_e32 v13, v6
	v_mov_b32_e32 v11, v7
	v_pk_add_f32 v[8:9], v[12:13], v[10:11]
	v_mov_b32_e32 v25, v33
	v_mov_b32_e32 v10, v28
	v_mov_b32_e32 v11, v29
	v_mov_b32_e32 v7, v23
	v_mov_b32_e32 v6, v9
	v_mov_b32_e32 v14, v162
	v_mov_b32_e32 v15, v163
	v_mov_b32_e32 v16, v164
	v_mov_b32_e32 v17, v165
